# scan: INV normaliser and first-half row-statistics LDS reads issued right after barrier B1 in one batch (wave 0), chains run without serial LDS round trips; same arithmetic order
# speedup vs baseline: 1.0035x; 1.0011x over previous
.LBB0_504:
	v_or_b32_e32 v100, v100, v99
	v_lshlrev_b32_e32 v160, 3, v130
	v_or_b32_e32 v72, v160, v98
	v_lshlrev_b32_e32 v132, 4, v100
	v_add_u32_e32 v101, s72, v72
	v_cvt_pk_bf16_f32 v66, v66, v67
	v_cvt_pk_bf16_f32 v67, v68, v69
	v_xor_b32_e32 v68, s73, v132
	v_add_u32_e32 v200, v101, v68
	v_xor_b32_e32 v68, s94, v132
	s_waitcnt vmcnt(0)
	s_waitcnt vmcnt(0) lgkmcnt(0)
	s_barrier
	v_cmp_gt_i32_e64 s[12:13], 64, v140
	v_lshl_add_u32 v103, v140, 2, 0
	v_add_u32_e32 v104, 0x21000, v103
	s_and_b64 s[22:23], s[90:91], s[12:13]
	s_and_saveexec_b64 s[2:3], s[22:23]
	v_add_u32_e32 v105, 0x20400, v103
	v_add_u32_e32 v106, 0x20c00, v103
	v_add_u32_e32 v107, 0x20800, v103
	ds_read2st64_b32 v[108:109], v104 offset1:2
	ds_read2st64_b32 v[110:111], v104 offset0:4 offset1:6
	ds_read_b32 v105, v105
	ds_read_b32 v106, v106
	ds_read_b32 v107, v107
	s_mov_b64 exec, s[2:3]
	ds_write_b64 v200, v[66:67]
	v_cvt_pk_bf16_f32 v66, v70, v71
	v_cvt_pk_bf16_f32 v67, v102, v73
	v_add_u32_e32 v201, v101, v68
	v_xor_b32_e32 v68, s95, v132
	v_cmp_gt_i32_e64 s[12:13], 64, v140
	ds_write_b64 v201, v[66:67]
	v_cvt_pk_bf16_f32 v66, v74, v75
	v_cvt_pk_bf16_f32 v67, v76, v77
	v_add_u32_e32 v202, v101, v68
	v_xor_b32_e32 v68, s78, v132
	s_and_b64 s[22:23], s[90:91], s[12:13]
	ds_write_b64 v202, v[66:67]
	v_cvt_pk_bf16_f32 v66, v78, v79
	v_cvt_pk_bf16_f32 v67, v80, v81
	v_add_u32_e32 v203, v101, v68
	ds_write_b64 v203, v[66:67]
	s_and_saveexec_b64 s[2:3], s[22:23]
	s_cbranch_execz .LBB0_506
	s_waitcnt lgkmcnt(4)
	v_add_f32_e32 v66, v108, v109
	v_add_f32_e32 v67, v110, v111
	v_add_f32_e32 v66, v66, v67
	v_fmac_f32_e32 v66, v105, v106
	v_max_f32_e32 v67, v107, v107
	v_max_f32_e64 v66, |v66|, v67
	v_div_scale_f32 v67, s[8:9], v66, v66, 1.0
	v_rcp_f32_e32 v68, v67
	s_nop 0
	v_fma_f32 v69, -v67, v68, 1.0
	v_fmac_f32_e32 v68, v69, v68
	v_div_scale_f32 v69, vcc, 1.0, v66, 1.0
	v_mul_f32_e32 v70, v69, v68
	v_fma_f32 v71, -v67, v70, v69
	v_fmac_f32_e32 v70, v71, v68
	v_fma_f32 v67, -v67, v70, v69
	v_div_fmas_f32 v67, v67, v68, v70
	v_div_fixup_f32 v66, v67, v66, 1.0
	v_add_u32_e32 v67, 0x20a00, v103
	ds_write_b32 v67, v66

.LBB0_540:
	s_lshl_b64 s[2:3], s[16:17], 2
	s_add_u32 s2, s81, s2
	v_add_u32_e32 v78, 64, v140
	s_addc_u32 s3, s40, s3
	s_add_i32 s16, 0, 0x21800
	s_add_i32 s17, 0, 0x27200
	s_waitcnt lgkmcnt(0)
	v_lshlrev_b32_e32 v79, 2, v78
	v_add_u32_e32 v217, s16, v79
	v_add_u32_e32 v218, s17, v79
	v_add_u32_e32 v79, 0x200, v141
	v_add_u32_e32 v211, s16, v79
	v_add_u32_e32 v212, s17, v79
	v_add_u32_e32 v79, 0x300, v141
	v_add_u32_e32 v213, s16, v79
	v_add_u32_e32 v214, s17, v79
	v_add_u32_e32 v79, 0x400, v141
	v_add_u32_e32 v207, s16, v79
	v_add_u32_e32 v208, s17, v79
	v_add_u32_e32 v79, 0x500, v141
	v_add_u32_e32 v209, s16, v79
	v_add_u32_e32 v210, s17, v79
	v_add_u32_e32 v79, 0x600, v141
	v_add_u32_e32 v215, s16, v141
	v_add_u32_e32 v216, s17, v141
	v_add_u32_e32 v190, s16, v79
	v_add_u32_e32 v204, s17, v79
	v_add_u32_e32 v79, 0x700, v141
	v_ashrrev_i32_e32 v141, 31, v140
	v_add_u32_e32 v205, s16, v79
	v_add_u32_e32 v206, s17, v79
	v_lshl_add_u64 v[130:131], v[140:141], 2, s[2:3]
	s_and_b64 s[2:3], s[24:25], s[12:13]
	s_barrier
	s_and_saveexec_b64 s[10:11], s[22:23]
	v_lshl_add_u32 v238, v78, 2, 0
	v_add_u32_e32 v242, 0x21000, v238
	v_add_u32_e32 v239, 0x20400, v238
	v_add_u32_e32 v240, 0x20c00, v238
	v_add_u32_e32 v241, 0x20800, v238
	ds_read2st64_b32 v[244:245], v242 offset1:2
	ds_read2st64_b32 v[246:247], v242 offset0:4 offset1:6
	ds_read_b32 v239, v239
	ds_read_b32 v240, v240
	ds_read_b32 v241, v241
	s_mov_b64 exec, s[10:11]
	s_and_saveexec_b64 s[10:11], s[2:3]
	s_cbranch_execz .LBB0_542
	ds_read_b32 v80, v215
	ds_read_b32 v132, v216
	ds_read_b32 v81, v217
	ds_read_b32 v133, v218
	ds_read_b32 v196, v211
	ds_read_b32 v198, v212
	ds_read_b32 v197, v213
	ds_read_b32 v199, v214
	ds_read_b32 v220, v207
	ds_read_b32 v222, v208
	ds_read_b32 v221, v209
	ds_read_b32 v223, v210
	ds_read_b32 v148, v190
	ds_read_b32 v252, v204
	ds_read_b32 v149, v205
	ds_read_b32 v253, v206
	s_waitcnt lgkmcnt(12)
	v_pk_add_f32 v[80:81], v[80:81], v[132:133]
	s_nop 0
	v_add_f32_e32 v79, 0, v80
	v_add_f32_e32 v79, v79, v81
	s_waitcnt lgkmcnt(8)
	v_pk_add_f32 v[196:197], v[196:197], v[198:199]
	s_nop 0
	v_add_f32_e32 v79, v79, v196
	v_add_f32_e32 v79, v79, v197
	s_waitcnt lgkmcnt(4)
	v_pk_add_f32 v[220:221], v[220:221], v[222:223]
	s_nop 0
	v_add_f32_e32 v79, v79, v220
	v_add_f32_e32 v79, v79, v221
	s_waitcnt lgkmcnt(0)
	v_pk_add_f32 v[148:149], v[148:149], v[252:253]
	s_nop 0
	v_add_f32_e32 v79, v79, v148
	v_add_f32_e32 v79, v79, v149
	global_store_dword v[130:131], v79, off
.LBB0_542:
	s_or_b64 exec, exec, s[10:11]
	v_cvt_pk_bf16_f32 v80, v134, v135
	v_cvt_pk_bf16_f32 v81, v136, v137
	v_cvt_pk_bf16_f32 v70, v70, v71
	v_cvt_pk_bf16_f32 v71, v72, v73
	ds_write_b64 v200, v[80:81]
	ds_write_b64 v201, v[70:71]
	v_cvt_pk_bf16_f32 v70, v74, v75
	v_cvt_pk_bf16_f32 v71, v76, v77
	v_cvt_pk_bf16_f32 v66, v66, v67
	v_cvt_pk_bf16_f32 v67, v68, v69
	ds_write_b64 v202, v[70:71]
	ds_write_b64 v203, v[66:67]
	s_and_saveexec_b64 s[10:11], s[22:23]
	s_cbranch_execz .LBB0_544
	s_waitcnt lgkmcnt(4)
	v_add_f32_e32 v66, v244, v245
	v_add_f32_e32 v67, v246, v247
	v_add_f32_e32 v66, v66, v67
	v_fmac_f32_e32 v66, v239, v240
	v_max_f32_e32 v67, v241, v241
	v_max_f32_e64 v66, |v66|, v67
	v_div_scale_f32 v67, s[12:13], v66, v66, 1.0
	v_rcp_f32_e32 v68, v67
	s_nop 0
	v_fma_f32 v69, -v67, v68, 1.0
	v_fmac_f32_e32 v68, v69, v68
	v_div_scale_f32 v69, vcc, 1.0, v66, 1.0
	v_mul_f32_e32 v70, v69, v68
	v_fma_f32 v71, -v67, v70, v69
	v_fmac_f32_e32 v70, v71, v68
	v_fma_f32 v67, -v67, v70, v69
	v_div_fmas_f32 v67, v67, v68, v70
	v_div_fixup_f32 v66, v67, v66, 1.0
	v_add_u32_e32 v67, 0x20a00, v238
	ds_write_b32 v67, v66

.LBB0_601:
	s_or_b64 exec, exec, s[2:3]
	s_barrier
	global_load_dwordx4 v[2:5], v[24:25], off offset:80
	global_load_dwordx4 v[10:13], v[24:25], off offset:64
	s_mov_b64 s[2:3], 0x10040
	v_add_co_u32_e32 v8, vcc, 0x10000, v20
	v_lshl_add_u64 v[6:7], v[20:21], 0, s[2:3]
	s_nop 0
	v_addc_co_u32_e32 v9, vcc, 0, v21, vcc
	global_load_dwordx4 v[14:17], v[8:9], off offset:64
	s_nop 0
	global_load_dwordx4 v[6:9], v[6:7], off offset:16
	v_mov_b32_e32 v48, v191
	v_mov_b32_e32 v49, v191
	s_waitcnt vmcnt(2)
	v_lshlrev_b32_e32 v26, 16, v10
	v_and_b32_e32 v27, 0xffff0000, v10
	v_pk_add_f32 v[26:27], v[26:27], 0 op_sel_hi:[1,0]
	s_waitcnt vmcnt(1)
	v_lshlrev_b32_e32 v28, 16, v14
	v_and_b32_e32 v29, 0xffff0000, v14
	v_pk_add_f32 v[28:29], v[26:27], v[28:29]
	v_lshlrev_b32_e32 v14, 16, v15
	v_cvt_pk_bf16_f32 v10, v28, s0
	s_mov_b32 s0, 0x41000
	v_add_co_u32_e32 v46, vcc, s0, v18
	v_and_b32_e32 v15, 0xffff0000, v15
	s_nop 0
	v_addc_co_u32_e32 v47, vcc, 0, v19, vcc
	global_store_short v[46:47], v10, off offset:-4096
	v_cvt_pk_bf16_f32 v10, v29, s0
	global_store_short v[46:47], v10, off
	v_lshlrev_b32_e32 v10, 16, v11
	v_and_b32_e32 v11, 0xffff0000, v11
	v_pk_add_f32 v[10:11], v[10:11], 0 op_sel_hi:[1,0]
	v_mov_b32_e32 v47, v191
	v_pk_add_f32 v[14:15], v[10:11], v[14:15]
	v_pk_mul_f32 v[26:27], v[28:29], v[28:29]
	v_cvt_pk_bf16_f32 v46, v14, s0
	s_mov_b32 s0, 0x42000
	v_add_co_u32_e32 v10, vcc, s0, v18
	v_mov_b32_dpp v48, v26 quad_perm:[1,0,3,2] row_mask:0xf bank_mask:0xf
	s_nop 0
	v_addc_co_u32_e32 v11, vcc, 0, v19, vcc
	global_store_short v[10:11], v46, off
	v_pk_mul_f32 v[10:11], v[14:15], v[14:15]
	v_mov_b32_e32 v46, v191
	v_mov_b32_dpp v49, v27 quad_perm:[1,0,3,2] row_mask:0xf bank_mask:0xf
	v_mov_b32_dpp v47, v11 quad_perm:[1,0,3,2] row_mask:0xf bank_mask:0xf
	v_mov_b32_dpp v46, v10 quad_perm:[1,0,3,2] row_mask:0xf bank_mask:0xf
	v_pk_fma_f32 v[10:11], v[14:15], v[14:15], v[46:47]
	v_mov_b32_e32 v46, v191
	v_mov_b32_e32 v47, v191
	v_pk_fma_f32 v[26:27], v[28:29], v[28:29], v[48:49]
	v_mov_b32_dpp v46, v10 quad_perm:[2,3,0,1] row_mask:0xf bank_mask:0xf
	v_mov_b32_dpp v47, v11 quad_perm:[2,3,0,1] row_mask:0xf bank_mask:0xf
	v_mov_b32_e32 v48, v191
	v_mov_b32_e32 v49, v191
	v_pk_add_f32 v[10:11], v[10:11], v[46:47]
	v_mov_b32_e32 v46, v191
	v_mov_b32_e32 v47, v191
	v_mov_b32_dpp v48, v26 quad_perm:[2,3,0,1] row_mask:0xf bank_mask:0xf
	v_mov_b32_dpp v49, v27 quad_perm:[2,3,0,1] row_mask:0xf bank_mask:0xf
	v_mov_b32_dpp v46, v10 row_half_mirror row_mask:0xf bank_mask:0xf
	v_mov_b32_dpp v47, v11 row_half_mirror row_mask:0xf bank_mask:0xf
	v_pk_add_f32 v[26:27], v[26:27], v[48:49]
	v_mov_b32_e32 v48, v191
	v_mov_b32_e32 v49, v191
	v_pk_add_f32 v[10:11], v[10:11], v[46:47]
	v_add_co_u32_e32 v46, vcc, 0x43000, v18
	v_mov_b32_dpp v48, v26 row_half_mirror row_mask:0xf bank_mask:0xf
	v_mov_b32_dpp v49, v27 row_half_mirror row_mask:0xf bank_mask:0xf
	v_cvt_pk_bf16_f32 v15, v15, s0
	v_addc_co_u32_e32 v47, vcc, 0, v19, vcc
	v_pk_add_f32 v[26:27], v[26:27], v[48:49]
	v_mov_b32_e32 v28, v191
	v_mov_b32_e32 v29, v191
	v_mov_b32_e32 v14, v191
	global_store_short v[46:47], v15, off
	v_mov_b32_e32 v15, v191
	v_mov_b32_dpp v28, v26 row_mirror row_mask:0xf bank_mask:0xf
	v_mov_b32_dpp v29, v27 row_mirror row_mask:0xf bank_mask:0xf
	v_mov_b32_dpp v14, v10 row_mirror row_mask:0xf bank_mask:0xf
	v_mov_b32_dpp v15, v11 row_mirror row_mask:0xf bank_mask:0xf
	s_and_saveexec_b64 s[2:3], s[6:7]
	v_pk_add_f32 v[48:49], v[10:11], v[14:15]
	v_pk_add_f32 v[46:47], v[26:27], v[28:29]
	ds_write_b128 v1, v[46:49]
	s_or_b64 exec, exec, s[2:3]
	v_lshlrev_b32_e32 v10, 16, v12
	v_and_b32_e32 v11, 0xffff0000, v12
	v_pk_add_f32 v[10:11], v[10:11], 0 op_sel_hi:[1,0]
	v_lshlrev_b32_e32 v14, 16, v16
	v_and_b32_e32 v15, 0xffff0000, v16
	v_pk_add_f32 v[10:11], v[10:11], v[14:15]
	v_lshlrev_b32_e32 v12, 16, v13
	v_and_b32_e32 v13, 0xffff0000, v13
	v_pk_add_f32 v[12:13], v[12:13], 0 op_sel_hi:[1,0]
	v_lshlrev_b32_e32 v14, 16, v17
	v_and_b32_e32 v15, 0xffff0000, v17
	v_cvt_pk_bf16_f32 v16, v10, s0
	s_mov_b32 s0, 0x49000
	v_pk_add_f32 v[14:15], v[12:13], v[14:15]
	v_add_co_u32_e32 v12, vcc, s0, v18
	v_mov_b32_e32 v26, v191
	s_nop 0
	v_addc_co_u32_e32 v13, vcc, 0, v19, vcc
	global_store_short v[12:13], v16, off offset:-4096
	v_pk_mul_f32 v[16:17], v[10:11], v[10:11]
	v_mov_b32_e32 v27, v191
	v_mov_b32_e32 v28, v191
	v_mov_b32_dpp v26, v16 quad_perm:[1,0,3,2] row_mask:0xf bank_mask:0xf
	v_mov_b32_dpp v27, v17 quad_perm:[1,0,3,2] row_mask:0xf bank_mask:0xf
	v_cvt_pk_bf16_f32 v16, v11, s0
	v_pk_fma_f32 v[10:11], v[10:11], v[10:11], v[26:27]
	v_cvt_pk_bf16_f32 v26, v14, s0
	s_mov_b32 s0, 0x4b000
	global_store_short v[12:13], v16, off
	v_add_co_u32_e32 v16, vcc, s0, v18
	v_mov_b32_e32 v29, v191
	s_nop 0
	v_addc_co_u32_e32 v17, vcc, 0, v19, vcc
	global_store_short v[16:17], v26, off offset:-4096
	v_pk_mul_f32 v[26:27], v[14:15], v[14:15]
	v_mov_b32_e32 v12, v191
	v_mov_b32_e32 v13, v191
	v_mov_b32_dpp v28, v26 quad_perm:[1,0,3,2] row_mask:0xf bank_mask:0xf
	v_cvt_pk_bf16_f32 v26, v15, s0
	v_mov_b32_dpp v29, v27 quad_perm:[1,0,3,2] row_mask:0xf bank_mask:0xf
	global_store_short v[16:17], v26, off
	v_pk_fma_f32 v[14:15], v[14:15], v[14:15], v[28:29]
	v_mov_b32_e32 v16, v191
	v_mov_b32_e32 v17, v191
	v_mov_b32_dpp v12, v10 quad_perm:[2,3,0,1] row_mask:0xf bank_mask:0xf
	v_mov_b32_dpp v13, v11 quad_perm:[2,3,0,1] row_mask:0xf bank_mask:0xf
	v_mov_b32_dpp v16, v14 quad_perm:[2,3,0,1] row_mask:0xf bank_mask:0xf
	v_mov_b32_dpp v17, v15 quad_perm:[2,3,0,1] row_mask:0xf bank_mask:0xf
	v_pk_add_f32 v[10:11], v[10:11], v[12:13]
	v_mov_b32_e32 v12, v191
	v_mov_b32_e32 v13, v191
	v_pk_add_f32 v[14:15], v[14:15], v[16:17]
	v_mov_b32_e32 v16, v191
	v_mov_b32_e32 v17, v191
	v_mov_b32_dpp v12, v10 row_half_mirror row_mask:0xf bank_mask:0xf
	v_mov_b32_dpp v13, v11 row_half_mirror row_mask:0xf bank_mask:0xf
	v_mov_b32_dpp v16, v14 row_half_mirror row_mask:0xf bank_mask:0xf
	v_mov_b32_dpp v17, v15 row_half_mirror row_mask:0xf bank_mask:0xf
	v_pk_add_f32 v[10:11], v[10:11], v[12:13]
	v_mov_b32_e32 v12, v191
	v_mov_b32_e32 v13, v191
	v_pk_add_f32 v[14:15], v[14:15], v[16:17]
	v_mov_b32_e32 v16, v191
	v_mov_b32_e32 v17, v191
	v_mov_b32_dpp v12, v10 row_mirror row_mask:0xf bank_mask:0xf
	v_mov_b32_dpp v13, v11 row_mirror row_mask:0xf bank_mask:0xf
	v_mov_b32_dpp v16, v14 row_mirror row_mask:0xf bank_mask:0xf
	v_mov_b32_dpp v17, v15 row_mirror row_mask:0xf bank_mask:0xf
	s_and_saveexec_b64 s[2:3], s[6:7]
	v_pk_add_f32 v[14:15], v[14:15], v[16:17]
	v_pk_add_f32 v[12:13], v[10:11], v[12:13]
	ds_write_b128 v1, v[12:15] offset:32
	s_or_b64 exec, exec, s[2:3]
	v_lshlrev_b32_e32 v10, 16, v2
	v_and_b32_e32 v11, 0xffff0000, v2
	v_pk_add_f32 v[10:11], v[10:11], 0 op_sel_hi:[1,0]
	s_waitcnt vmcnt(8)
	v_lshlrev_b32_e32 v12, 16, v6
	v_and_b32_e32 v13, 0xffff0000, v6
	v_lshlrev_b32_e32 v2, 16, v3
	v_and_b32_e32 v3, 0xffff0000, v3
	v_pk_add_f32 v[10:11], v[10:11], v[12:13]
	v_pk_add_f32 v[2:3], v[2:3], 0 op_sel_hi:[1,0]
	v_lshlrev_b32_e32 v6, 16, v7
	v_and_b32_e32 v7, 0xffff0000, v7
	v_pk_add_f32 v[12:13], v[2:3], v[6:7]
	v_cvt_pk_bf16_f32 v6, v10, s0
	s_mov_b32 s0, 0x51000
	v_add_co_u32_e32 v2, vcc, s0, v18
	v_mov_b32_e32 v14, v191
	s_nop 0
	v_addc_co_u32_e32 v3, vcc, 0, v19, vcc
	global_store_short v[2:3], v6, off offset:-4096
	v_pk_mul_f32 v[6:7], v[10:11], v[10:11]
	v_mov_b32_e32 v15, v191
	v_mov_b32_e32 v16, v191
	v_mov_b32_dpp v14, v6 quad_perm:[1,0,3,2] row_mask:0xf bank_mask:0xf
	v_cvt_pk_bf16_f32 v6, v11, s0
	v_mov_b32_dpp v15, v7 quad_perm:[1,0,3,2] row_mask:0xf bank_mask:0xf
	global_store_short v[2:3], v6, off
	v_pk_fma_f32 v[2:3], v[10:11], v[10:11], v[14:15]
	v_cvt_pk_bf16_f32 v14, v12, s0
	s_mov_b32 s0, 0x53000
	v_add_co_u32_e32 v10, vcc, s0, v18
	v_mov_b32_e32 v17, v191
	s_nop 0
	v_addc_co_u32_e32 v11, vcc, 0, v19, vcc
	global_store_short v[10:11], v14, off offset:-4096
	v_pk_mul_f32 v[14:15], v[12:13], v[12:13]
	v_mov_b32_e32 v6, v191
	v_mov_b32_e32 v7, v191
	v_mov_b32_dpp v16, v14 quad_perm:[1,0,3,2] row_mask:0xf bank_mask:0xf
	v_cvt_pk_bf16_f32 v14, v13, s0
	v_mov_b32_dpp v17, v15 quad_perm:[1,0,3,2] row_mask:0xf bank_mask:0xf
	global_store_short v[10:11], v14, off
	v_pk_fma_f32 v[10:11], v[12:13], v[12:13], v[16:17]
	v_mov_b32_e32 v12, v191
	v_mov_b32_e32 v13, v191
	v_mov_b32_dpp v6, v2 quad_perm:[2,3,0,1] row_mask:0xf bank_mask:0xf
	v_mov_b32_dpp v7, v3 quad_perm:[2,3,0,1] row_mask:0xf bank_mask:0xf
	v_mov_b32_dpp v12, v10 quad_perm:[2,3,0,1] row_mask:0xf bank_mask:0xf
	v_mov_b32_dpp v13, v11 quad_perm:[2,3,0,1] row_mask:0xf bank_mask:0xf
	v_pk_add_f32 v[2:3], v[2:3], v[6:7]
	v_mov_b32_e32 v6, v191
	v_mov_b32_e32 v7, v191
	v_pk_add_f32 v[10:11], v[10:11], v[12:13]
	v_mov_b32_e32 v12, v191
	v_mov_b32_e32 v13, v191
	v_mov_b32_dpp v6, v2 row_half_mirror row_mask:0xf bank_mask:0xf
	v_mov_b32_dpp v7, v3 row_half_mirror row_mask:0xf bank_mask:0xf
	v_mov_b32_dpp v12, v10 row_half_mirror row_mask:0xf bank_mask:0xf
	v_mov_b32_dpp v13, v11 row_half_mirror row_mask:0xf bank_mask:0xf
	v_pk_add_f32 v[2:3], v[2:3], v[6:7]
	v_mov_b32_e32 v6, v191
	v_mov_b32_e32 v7, v191
	v_pk_add_f32 v[10:11], v[10:11], v[12:13]
	v_mov_b32_e32 v12, v191
	v_mov_b32_e32 v13, v191
	v_mov_b32_dpp v6, v2 row_mirror row_mask:0xf bank_mask:0xf
	v_mov_b32_dpp v7, v3 row_mirror row_mask:0xf bank_mask:0xf
	v_mov_b32_dpp v12, v10 row_mirror row_mask:0xf bank_mask:0xf
	v_mov_b32_dpp v13, v11 row_mirror row_mask:0xf bank_mask:0xf
	s_and_saveexec_b64 s[2:3], s[6:7]
	v_pk_add_f32 v[12:13], v[10:11], v[12:13]
	v_pk_add_f32 v[10:11], v[2:3], v[6:7]
	ds_write_b128 v1, v[10:13] offset:64
	s_or_b64 exec, exec, s[2:3]
	v_lshlrev_b32_e32 v2, 16, v4
	v_and_b32_e32 v3, 0xffff0000, v4
	v_pk_add_f32 v[2:3], v[2:3], 0 op_sel_hi:[1,0]
	v_lshlrev_b32_e32 v6, 16, v8
	v_and_b32_e32 v7, 0xffff0000, v8
	v_pk_add_f32 v[2:3], v[2:3], v[6:7]
	v_lshlrev_b32_e32 v4, 16, v5
	v_and_b32_e32 v5, 0xffff0000, v5
	v_pk_add_f32 v[4:5], v[4:5], 0 op_sel_hi:[1,0]
	v_lshlrev_b32_e32 v6, 16, v9
	v_and_b32_e32 v7, 0xffff0000, v9
	v_cvt_pk_bf16_f32 v8, v2, s0
	s_mov_b32 s0, 0x59000
	v_pk_add_f32 v[6:7], v[4:5], v[6:7]
	v_add_co_u32_e32 v4, vcc, s0, v18
	v_mov_b32_e32 v10, v191
	s_nop 0
	v_addc_co_u32_e32 v5, vcc, 0, v19, vcc
	global_store_short v[4:5], v8, off offset:-4096
	v_pk_mul_f32 v[8:9], v[2:3], v[2:3]
	v_mov_b32_e32 v11, v191
	v_mov_b32_e32 v12, v191
	v_mov_b32_dpp v10, v8 quad_perm:[1,0,3,2] row_mask:0xf bank_mask:0xf
	v_mov_b32_dpp v11, v9 quad_perm:[1,0,3,2] row_mask:0xf bank_mask:0xf
	v_cvt_pk_bf16_f32 v8, v3, s0
	v_pk_fma_f32 v[2:3], v[2:3], v[2:3], v[10:11]
	v_cvt_pk_bf16_f32 v10, v6, s0
	s_mov_b32 s0, 0x5b000
	global_store_short v[4:5], v8, off
	v_add_co_u32_e32 v8, vcc, s0, v18
	v_mov_b32_e32 v13, v191
	s_nop 0
	v_addc_co_u32_e32 v9, vcc, 0, v19, vcc
	global_store_short v[8:9], v10, off offset:-4096
	v_pk_mul_f32 v[10:11], v[6:7], v[6:7]
	v_mov_b32_e32 v4, v191
	v_mov_b32_e32 v5, v191
	v_mov_b32_dpp v12, v10 quad_perm:[1,0,3,2] row_mask:0xf bank_mask:0xf
	v_cvt_pk_bf16_f32 v10, v7, s0
	v_mov_b32_dpp v13, v11 quad_perm:[1,0,3,2] row_mask:0xf bank_mask:0xf
	global_store_short v[8:9], v10, off
	v_pk_fma_f32 v[6:7], v[6:7], v[6:7], v[12:13]
	v_mov_b32_e32 v8, v191
	v_mov_b32_e32 v9, v191
	v_mov_b32_dpp v4, v2 quad_perm:[2,3,0,1] row_mask:0xf bank_mask:0xf
	v_mov_b32_dpp v5, v3 quad_perm:[2,3,0,1] row_mask:0xf bank_mask:0xf
	v_mov_b32_dpp v8, v6 quad_perm:[2,3,0,1] row_mask:0xf bank_mask:0xf
	v_mov_b32_dpp v9, v7 quad_perm:[2,3,0,1] row_mask:0xf bank_mask:0xf
	v_pk_add_f32 v[2:3], v[2:3], v[4:5]
	v_mov_b32_e32 v4, v191
	v_mov_b32_e32 v5, v191
	v_pk_add_f32 v[6:7], v[6:7], v[8:9]
	v_mov_b32_e32 v8, v191
	v_mov_b32_e32 v9, v191
	v_mov_b32_dpp v4, v2 row_half_mirror row_mask:0xf bank_mask:0xf
	v_mov_b32_dpp v5, v3 row_half_mirror row_mask:0xf bank_mask:0xf
	v_mov_b32_dpp v8, v6 row_half_mirror row_mask:0xf bank_mask:0xf
	v_mov_b32_dpp v9, v7 row_half_mirror row_mask:0xf bank_mask:0xf
	v_pk_add_f32 v[2:3], v[2:3], v[4:5]
	v_mov_b32_e32 v4, v191
	v_mov_b32_e32 v5, v191
	v_pk_add_f32 v[6:7], v[6:7], v[8:9]
	v_mov_b32_e32 v8, v191
	v_mov_b32_e32 v9, v191
	v_mov_b32_dpp v4, v2 row_mirror row_mask:0xf bank_mask:0xf
	v_mov_b32_dpp v5, v3 row_mirror row_mask:0xf bank_mask:0xf
	v_mov_b32_dpp v8, v6 row_mirror row_mask:0xf bank_mask:0xf
	v_mov_b32_dpp v9, v7 row_mirror row_mask:0xf bank_mask:0xf
	s_and_saveexec_b64 s[2:3], s[6:7]
	v_pk_add_f32 v[6:7], v[6:7], v[8:9]
	v_pk_add_f32 v[4:5], v[2:3], v[4:5]
	ds_write_b128 v1, v[4:7] offset:96
	s_or_b64 exec, exec, s[2:3]
	global_load_dwordx4 v[2:5], v[24:25], off offset:112
	global_load_dwordx4 v[10:13], v[24:25], off offset:96
	s_mov_b64 s[2:3], 0x10060
	v_add_co_u32_e32 v8, vcc, 0x10000, v20
	v_lshl_add_u64 v[6:7], v[20:21], 0, s[2:3]
	s_nop 0
	v_addc_co_u32_e32 v9, vcc, 0, v21, vcc
	global_load_dwordx4 v[14:17], v[8:9], off offset:96
	s_nop 0
	global_load_dwordx4 v[6:9], v[6:7], off offset:16
	v_mov_b32_e32 v28, v191
	v_mov_b32_e32 v29, v191
	s_waitcnt vmcnt(2)
	v_lshlrev_b32_e32 v20, 16, v10
	v_and_b32_e32 v21, 0xffff0000, v10
	v_pk_add_f32 v[20:21], v[20:21], 0 op_sel_hi:[1,0]
	s_waitcnt vmcnt(1)
	v_lshlrev_b32_e32 v24, 16, v14
	v_and_b32_e32 v25, 0xffff0000, v14
	v_pk_add_f32 v[24:25], v[20:21], v[24:25]
	v_lshlrev_b32_e32 v14, 16, v15
	v_cvt_pk_bf16_f32 v10, v24, s0
	s_mov_b32 s0, 0x61000
	v_add_co_u32_e32 v26, vcc, s0, v18
	v_and_b32_e32 v15, 0xffff0000, v15
	s_nop 0
	v_addc_co_u32_e32 v27, vcc, 0, v19, vcc
	global_store_short v[26:27], v10, off offset:-4096
	v_cvt_pk_bf16_f32 v10, v25, s0
	global_store_short v[26:27], v10, off
	v_lshlrev_b32_e32 v10, 16, v11
	v_and_b32_e32 v11, 0xffff0000, v11
	v_pk_add_f32 v[10:11], v[10:11], 0 op_sel_hi:[1,0]
	v_mov_b32_e32 v27, v191
	v_pk_add_f32 v[14:15], v[10:11], v[14:15]
	v_pk_mul_f32 v[20:21], v[24:25], v[24:25]
	v_cvt_pk_bf16_f32 v26, v14, s0
	s_mov_b32 s0, 0x62000
	v_add_co_u32_e32 v10, vcc, s0, v18
	v_mov_b32_dpp v28, v20 quad_perm:[1,0,3,2] row_mask:0xf bank_mask:0xf
	s_nop 0
	v_addc_co_u32_e32 v11, vcc, 0, v19, vcc
	global_store_short v[10:11], v26, off
	v_pk_mul_f32 v[10:11], v[14:15], v[14:15]
	v_mov_b32_e32 v26, v191
	v_mov_b32_dpp v29, v21 quad_perm:[1,0,3,2] row_mask:0xf bank_mask:0xf
	v_mov_b32_dpp v27, v11 quad_perm:[1,0,3,2] row_mask:0xf bank_mask:0xf
	v_mov_b32_dpp v26, v10 quad_perm:[1,0,3,2] row_mask:0xf bank_mask:0xf
	v_pk_fma_f32 v[10:11], v[14:15], v[14:15], v[26:27]
	v_mov_b32_e32 v26, v191
	v_mov_b32_e32 v27, v191
	v_pk_fma_f32 v[20:21], v[24:25], v[24:25], v[28:29]
	v_mov_b32_dpp v26, v10 quad_perm:[2,3,0,1] row_mask:0xf bank_mask:0xf
	v_mov_b32_dpp v27, v11 quad_perm:[2,3,0,1] row_mask:0xf bank_mask:0xf
	v_mov_b32_e32 v28, v191
	v_mov_b32_e32 v29, v191
	v_pk_add_f32 v[10:11], v[10:11], v[26:27]
	v_mov_b32_e32 v26, v191
	v_mov_b32_e32 v27, v191
	v_mov_b32_dpp v28, v20 quad_perm:[2,3,0,1] row_mask:0xf bank_mask:0xf
	v_mov_b32_dpp v29, v21 quad_perm:[2,3,0,1] row_mask:0xf bank_mask:0xf
	v_mov_b32_dpp v26, v10 row_half_mirror row_mask:0xf bank_mask:0xf
	v_mov_b32_dpp v27, v11 row_half_mirror row_mask:0xf bank_mask:0xf
	v_pk_add_f32 v[20:21], v[20:21], v[28:29]
	v_mov_b32_e32 v28, v191
	v_mov_b32_e32 v29, v191
	v_pk_add_f32 v[10:11], v[10:11], v[26:27]
	v_add_co_u32_e32 v26, vcc, 0x63000, v18
	v_mov_b32_dpp v28, v20 row_half_mirror row_mask:0xf bank_mask:0xf
	v_mov_b32_dpp v29, v21 row_half_mirror row_mask:0xf bank_mask:0xf
	v_cvt_pk_bf16_f32 v15, v15, s0
	v_addc_co_u32_e32 v27, vcc, 0, v19, vcc
	v_pk_add_f32 v[20:21], v[20:21], v[28:29]
	v_mov_b32_e32 v24, v191
	v_mov_b32_e32 v25, v191
	v_mov_b32_e32 v14, v191
	global_store_short v[26:27], v15, off
	v_mov_b32_e32 v15, v191
	v_mov_b32_dpp v24, v20 row_mirror row_mask:0xf bank_mask:0xf
	v_mov_b32_dpp v25, v21 row_mirror row_mask:0xf bank_mask:0xf
	v_mov_b32_dpp v14, v10 row_mirror row_mask:0xf bank_mask:0xf
	v_mov_b32_dpp v15, v11 row_mirror row_mask:0xf bank_mask:0xf
	s_and_saveexec_b64 s[2:3], s[6:7]
	v_pk_add_f32 v[26:27], v[10:11], v[14:15]
	v_pk_add_f32 v[24:25], v[20:21], v[24:25]
	ds_write_b128 v1, v[24:27] offset:128
	s_or_b64 exec, exec, s[2:3]
	v_lshlrev_b32_e32 v10, 16, v12
	v_and_b32_e32 v11, 0xffff0000, v12
	v_pk_add_f32 v[10:11], v[10:11], 0 op_sel_hi:[1,0]
	v_lshlrev_b32_e32 v14, 16, v16
	v_and_b32_e32 v15, 0xffff0000, v16
	v_pk_add_f32 v[10:11], v[10:11], v[14:15]
	v_lshlrev_b32_e32 v12, 16, v13
	v_and_b32_e32 v13, 0xffff0000, v13
	v_pk_add_f32 v[12:13], v[12:13], 0 op_sel_hi:[1,0]
	v_lshlrev_b32_e32 v14, 16, v17
	v_and_b32_e32 v15, 0xffff0000, v17
	v_cvt_pk_bf16_f32 v16, v10, s0
	s_mov_b32 s0, 0x69000
	v_pk_add_f32 v[14:15], v[12:13], v[14:15]
	v_add_co_u32_e32 v12, vcc, s0, v18
	v_mov_b32_e32 v20, v191
	s_nop 0
	v_addc_co_u32_e32 v13, vcc, 0, v19, vcc
	global_store_short v[12:13], v16, off offset:-4096
	v_pk_mul_f32 v[16:17], v[10:11], v[10:11]
	v_mov_b32_e32 v21, v191
	v_mov_b32_e32 v24, v191
	v_mov_b32_dpp v20, v16 quad_perm:[1,0,3,2] row_mask:0xf bank_mask:0xf
	v_mov_b32_dpp v21, v17 quad_perm:[1,0,3,2] row_mask:0xf bank_mask:0xf
	v_cvt_pk_bf16_f32 v16, v11, s0
	v_pk_fma_f32 v[10:11], v[10:11], v[10:11], v[20:21]
	v_cvt_pk_bf16_f32 v20, v14, s0
	s_mov_b32 s0, 0x6b000
	global_store_short v[12:13], v16, off
	v_add_co_u32_e32 v16, vcc, s0, v18
	v_mov_b32_e32 v25, v191
	s_nop 0
	v_addc_co_u32_e32 v17, vcc, 0, v19, vcc
	global_store_short v[16:17], v20, off offset:-4096
	v_pk_mul_f32 v[20:21], v[14:15], v[14:15]
	v_mov_b32_e32 v12, v191
	v_mov_b32_e32 v13, v191
	v_mov_b32_dpp v24, v20 quad_perm:[1,0,3,2] row_mask:0xf bank_mask:0xf
	v_cvt_pk_bf16_f32 v20, v15, s0
	v_mov_b32_dpp v25, v21 quad_perm:[1,0,3,2] row_mask:0xf bank_mask:0xf
	global_store_short v[16:17], v20, off
	v_pk_fma_f32 v[14:15], v[14:15], v[14:15], v[24:25]
	v_mov_b32_e32 v16, v191
	v_mov_b32_e32 v17, v191
	v_mov_b32_dpp v12, v10 quad_perm:[2,3,0,1] row_mask:0xf bank_mask:0xf
	v_mov_b32_dpp v13, v11 quad_perm:[2,3,0,1] row_mask:0xf bank_mask:0xf
	v_mov_b32_dpp v16, v14 quad_perm:[2,3,0,1] row_mask:0xf bank_mask:0xf
	v_mov_b32_dpp v17, v15 quad_perm:[2,3,0,1] row_mask:0xf bank_mask:0xf
	v_pk_add_f32 v[10:11], v[10:11], v[12:13]
	v_mov_b32_e32 v12, v191
	v_mov_b32_e32 v13, v191
	v_pk_add_f32 v[14:15], v[14:15], v[16:17]
	v_mov_b32_e32 v16, v191
	v_mov_b32_e32 v17, v191
	v_mov_b32_dpp v12, v10 row_half_mirror row_mask:0xf bank_mask:0xf
	v_mov_b32_dpp v13, v11 row_half_mirror row_mask:0xf bank_mask:0xf
	v_mov_b32_dpp v16, v14 row_half_mirror row_mask:0xf bank_mask:0xf
	v_mov_b32_dpp v17, v15 row_half_mirror row_mask:0xf bank_mask:0xf
	v_pk_add_f32 v[10:11], v[10:11], v[12:13]
	v_mov_b32_e32 v12, v191
	v_mov_b32_e32 v13, v191
	v_pk_add_f32 v[14:15], v[14:15], v[16:17]
	v_mov_b32_e32 v16, v191
	v_mov_b32_e32 v17, v191
	v_mov_b32_dpp v12, v10 row_mirror row_mask:0xf bank_mask:0xf
	v_mov_b32_dpp v13, v11 row_mirror row_mask:0xf bank_mask:0xf
	v_mov_b32_dpp v16, v14 row_mirror row_mask:0xf bank_mask:0xf
	v_mov_b32_dpp v17, v15 row_mirror row_mask:0xf bank_mask:0xf
	s_and_saveexec_b64 s[2:3], s[6:7]
	v_pk_add_f32 v[14:15], v[14:15], v[16:17]
	v_pk_add_f32 v[12:13], v[10:11], v[12:13]
	ds_write_b128 v1, v[12:15] offset:160
	s_or_b64 exec, exec, s[2:3]
	v_lshlrev_b32_e32 v10, 16, v2
	v_and_b32_e32 v11, 0xffff0000, v2
	v_pk_add_f32 v[10:11], v[10:11], 0 op_sel_hi:[1,0]
	s_waitcnt vmcnt(8)
	v_lshlrev_b32_e32 v12, 16, v6
	v_and_b32_e32 v13, 0xffff0000, v6
	v_lshlrev_b32_e32 v2, 16, v3
	v_and_b32_e32 v3, 0xffff0000, v3
	v_pk_add_f32 v[10:11], v[10:11], v[12:13]
	v_pk_add_f32 v[2:3], v[2:3], 0 op_sel_hi:[1,0]
	v_lshlrev_b32_e32 v6, 16, v7
	v_and_b32_e32 v7, 0xffff0000, v7
	v_pk_add_f32 v[12:13], v[2:3], v[6:7]
	v_cvt_pk_bf16_f32 v6, v10, s0
	s_mov_b32 s0, 0x71000
	v_add_co_u32_e32 v2, vcc, s0, v18
	v_mov_b32_e32 v14, v191
	s_nop 0
	v_addc_co_u32_e32 v3, vcc, 0, v19, vcc
	global_store_short v[2:3], v6, off offset:-4096
	v_pk_mul_f32 v[6:7], v[10:11], v[10:11]
	v_mov_b32_e32 v15, v191
	v_mov_b32_e32 v16, v191
	v_mov_b32_dpp v14, v6 quad_perm:[1,0,3,2] row_mask:0xf bank_mask:0xf
	v_cvt_pk_bf16_f32 v6, v11, s0
	v_mov_b32_dpp v15, v7 quad_perm:[1,0,3,2] row_mask:0xf bank_mask:0xf
	global_store_short v[2:3], v6, off
	v_pk_fma_f32 v[2:3], v[10:11], v[10:11], v[14:15]
	v_cvt_pk_bf16_f32 v14, v12, s0
	s_mov_b32 s0, 0x73000
	v_add_co_u32_e32 v10, vcc, s0, v18
	v_mov_b32_e32 v17, v191
	s_nop 0
	v_addc_co_u32_e32 v11, vcc, 0, v19, vcc
	global_store_short v[10:11], v14, off offset:-4096
	v_pk_mul_f32 v[14:15], v[12:13], v[12:13]
	v_mov_b32_e32 v6, v191
	v_mov_b32_e32 v7, v191
	v_mov_b32_dpp v16, v14 quad_perm:[1,0,3,2] row_mask:0xf bank_mask:0xf
	v_cvt_pk_bf16_f32 v14, v13, s0
	v_mov_b32_dpp v17, v15 quad_perm:[1,0,3,2] row_mask:0xf bank_mask:0xf
	global_store_short v[10:11], v14, off
	v_pk_fma_f32 v[10:11], v[12:13], v[12:13], v[16:17]
	v_mov_b32_e32 v12, v191
	v_mov_b32_e32 v13, v191
	v_mov_b32_dpp v6, v2 quad_perm:[2,3,0,1] row_mask:0xf bank_mask:0xf
	v_mov_b32_dpp v7, v3 quad_perm:[2,3,0,1] row_mask:0xf bank_mask:0xf
	v_mov_b32_dpp v12, v10 quad_perm:[2,3,0,1] row_mask:0xf bank_mask:0xf
	v_mov_b32_dpp v13, v11 quad_perm:[2,3,0,1] row_mask:0xf bank_mask:0xf
	v_pk_add_f32 v[2:3], v[2:3], v[6:7]
	v_mov_b32_e32 v6, v191
	v_mov_b32_e32 v7, v191
	v_pk_add_f32 v[10:11], v[10:11], v[12:13]
	v_mov_b32_e32 v12, v191
	v_mov_b32_e32 v13, v191
	v_mov_b32_dpp v6, v2 row_half_mirror row_mask:0xf bank_mask:0xf
	v_mov_b32_dpp v7, v3 row_half_mirror row_mask:0xf bank_mask:0xf
	v_mov_b32_dpp v12, v10 row_half_mirror row_mask:0xf bank_mask:0xf
	v_mov_b32_dpp v13, v11 row_half_mirror row_mask:0xf bank_mask:0xf
	v_pk_add_f32 v[2:3], v[2:3], v[6:7]
	v_mov_b32_e32 v6, v191
	v_mov_b32_e32 v7, v191
	v_pk_add_f32 v[10:11], v[10:11], v[12:13]
	v_mov_b32_e32 v12, v191
	v_mov_b32_e32 v13, v191
	v_mov_b32_dpp v6, v2 row_mirror row_mask:0xf bank_mask:0xf
	v_mov_b32_dpp v7, v3 row_mirror row_mask:0xf bank_mask:0xf
	v_mov_b32_dpp v12, v10 row_mirror row_mask:0xf bank_mask:0xf
	v_mov_b32_dpp v13, v11 row_mirror row_mask:0xf bank_mask:0xf
	s_and_saveexec_b64 s[2:3], s[6:7]
	v_pk_add_f32 v[12:13], v[10:11], v[12:13]
	v_pk_add_f32 v[10:11], v[2:3], v[6:7]
	ds_write_b128 v1, v[10:13] offset:192
	s_or_b64 exec, exec, s[2:3]
	v_lshlrev_b32_e32 v2, 16, v4
	v_and_b32_e32 v3, 0xffff0000, v4
	v_pk_add_f32 v[2:3], v[2:3], 0 op_sel_hi:[1,0]
	v_lshlrev_b32_e32 v6, 16, v8
	v_and_b32_e32 v7, 0xffff0000, v8
	v_pk_add_f32 v[2:3], v[2:3], v[6:7]
	v_lshlrev_b32_e32 v4, 16, v5
	v_and_b32_e32 v5, 0xffff0000, v5
	v_pk_add_f32 v[4:5], v[4:5], 0 op_sel_hi:[1,0]
	v_lshlrev_b32_e32 v6, 16, v9
	v_and_b32_e32 v7, 0xffff0000, v9
	v_cvt_pk_bf16_f32 v8, v2, s0
	s_mov_b32 s0, 0x79000
	v_pk_add_f32 v[6:7], v[4:5], v[6:7]
	v_add_co_u32_e32 v4, vcc, s0, v18
	v_mov_b32_e32 v10, v191
	s_nop 0
	v_addc_co_u32_e32 v5, vcc, 0, v19, vcc
	global_store_short v[4:5], v8, off offset:-4096
	v_pk_mul_f32 v[8:9], v[2:3], v[2:3]
	v_mov_b32_e32 v11, v191
	v_mov_b32_e32 v12, v191
	v_mov_b32_dpp v10, v8 quad_perm:[1,0,3,2] row_mask:0xf bank_mask:0xf
	v_mov_b32_dpp v11, v9 quad_perm:[1,0,3,2] row_mask:0xf bank_mask:0xf
	v_cvt_pk_bf16_f32 v8, v3, s0
	v_pk_fma_f32 v[2:3], v[2:3], v[2:3], v[10:11]
	v_cvt_pk_bf16_f32 v10, v6, s0
	s_mov_b32 s0, 0x7b000
	global_store_short v[4:5], v8, off
	v_add_co_u32_e32 v8, vcc, s0, v18
	v_mov_b32_e32 v13, v191
	s_nop 0
	v_addc_co_u32_e32 v9, vcc, 0, v19, vcc
	global_store_short v[8:9], v10, off offset:-4096
	v_pk_mul_f32 v[10:11], v[6:7], v[6:7]
	v_mov_b32_e32 v4, v191
	v_mov_b32_e32 v5, v191
	v_mov_b32_dpp v12, v10 quad_perm:[1,0,3,2] row_mask:0xf bank_mask:0xf
	v_cvt_pk_bf16_f32 v10, v7, s0
	v_mov_b32_dpp v13, v11 quad_perm:[1,0,3,2] row_mask:0xf bank_mask:0xf
	global_store_short v[8:9], v10, off
	v_pk_fma_f32 v[6:7], v[6:7], v[6:7], v[12:13]
	v_mov_b32_e32 v8, v191
	v_mov_b32_e32 v9, v191
	v_mov_b32_dpp v4, v2 quad_perm:[2,3,0,1] row_mask:0xf bank_mask:0xf
	v_mov_b32_dpp v5, v3 quad_perm:[2,3,0,1] row_mask:0xf bank_mask:0xf
	v_mov_b32_dpp v8, v6 quad_perm:[2,3,0,1] row_mask:0xf bank_mask:0xf
	v_mov_b32_dpp v9, v7 quad_perm:[2,3,0,1] row_mask:0xf bank_mask:0xf
	v_pk_add_f32 v[2:3], v[2:3], v[4:5]
	v_mov_b32_e32 v4, v191
	v_mov_b32_e32 v5, v191
	v_pk_add_f32 v[6:7], v[6:7], v[8:9]
	v_mov_b32_e32 v8, v191
	v_mov_b32_e32 v9, v191
	v_mov_b32_dpp v4, v2 row_half_mirror row_mask:0xf bank_mask:0xf
	v_mov_b32_dpp v5, v3 row_half_mirror row_mask:0xf bank_mask:0xf
	v_mov_b32_dpp v8, v6 row_half_mirror row_mask:0xf bank_mask:0xf
	v_mov_b32_dpp v9, v7 row_half_mirror row_mask:0xf bank_mask:0xf
	v_pk_add_f32 v[2:3], v[2:3], v[4:5]
	v_mov_b32_e32 v4, v191
	v_mov_b32_e32 v5, v191
	v_pk_add_f32 v[6:7], v[6:7], v[8:9]
	v_mov_b32_e32 v8, v191
	v_mov_b32_e32 v9, v191
	v_mov_b32_dpp v4, v2 row_mirror row_mask:0xf bank_mask:0xf
	v_mov_b32_dpp v5, v3 row_mirror row_mask:0xf bank_mask:0xf
	v_mov_b32_dpp v8, v6 row_mirror row_mask:0xf bank_mask:0xf
	v_mov_b32_dpp v9, v7 row_mirror row_mask:0xf bank_mask:0xf
	s_and_saveexec_b64 s[2:3], s[6:7]
	v_pk_add_f32 v[6:7], v[6:7], v[8:9]
	v_pk_add_f32 v[4:5], v[2:3], v[4:5]
	ds_write_b128 v1, v[4:7] offset:224
	s_or_b64 exec, exec, s[2:3]
	s_waitcnt lgkmcnt(0)
	s_barrier
	s_and_saveexec_b64 s[2:3], s[8:9]
	s_cbranch_execz .LBB0_419
	ds_read_b32 v2, v42
	ds_read_b32 v4, v43
	ds_read_b32 v3, v44
	ds_read_b32 v5, v45
	s_waitcnt lgkmcnt(0)
	v_pk_add_f32 v[2:3], v[2:3], v[4:5]
	s_nop 0
	v_add_f32_e32 v1, 0, v2
	v_add_f32_e32 v1, v1, v3
	ds_read_b32 v2, v38
	ds_read_b32 v4, v39
	ds_read_b32 v3, v40
	ds_read_b32 v5, v41
	s_waitcnt lgkmcnt(0)
	v_pk_add_f32 v[2:3], v[2:3], v[4:5]
	s_nop 0
	v_add_f32_e32 v1, v1, v2
	v_add_f32_e32 v1, v1, v3
	ds_read_b32 v2, v34
	ds_read_b32 v4, v35
	ds_read_b32 v3, v36
	ds_read_b32 v5, v37
	s_waitcnt lgkmcnt(0)
	v_pk_add_f32 v[2:3], v[2:3], v[4:5]
	s_nop 0
	v_add_f32_e32 v1, v1, v2
	v_add_f32_e32 v1, v1, v3
	ds_read_b32 v2, v30
	ds_read_b32 v4, v31
	ds_read_b32 v3, v32
	ds_read_b32 v5, v33
	s_waitcnt lgkmcnt(0)
	v_pk_add_f32 v[2:3], v[2:3], v[4:5]
	s_nop 0
	v_add_f32_e32 v1, v1, v2
	v_add_f32_e32 v1, v1, v3
	global_store_dword v[22:23], v1, off offset:256
	s_branch .LBB0_419
	s_nop 0
	s_nop 0
	s_nop 0
	s_nop 0
	s_nop 0
	s_nop 0
	s_nop 0
	s_nop 0
	s_nop 0
	s_nop 0
	s_nop 0
	s_nop 0
	s_nop 0
	s_nop 0
	s_nop 0
	s_nop 0
